# compressed pass 2: V tile loads issued inside the QK MFMA shadow (plus window-loop K copy removal)
# speedup vs baseline: 1.0093x; 1.0048x over previous
; __device__ __forceinline__ void nsa_unit(const Params& p, int bg, int jq, LAS unsigned char* lds, int wave, int lane, bool build_lut) {
;     ...
;         if (ntile > 0) load_k(kn, kcmp, lane);
;         for (int T = 0; T < ntile; ++T) {
; #pragma unroll
;             for (int ks = 0; ks < 4; ++ks) kf[ks] = kn[ks];
;             load_v(vf, vcmpT + (size_t)T * 2048, lane);
;             if (T + 1 < ntile) load_k(kn, kcmp + (size_t)(T + 1) * 2048, lane);
;             f32x16 s = qk_tile(kf, qf);
.LBB0_1095:
.LBB0_1097:
	s_waitcnt vmcnt(0)
	v_mfma_f32_32x32x16_bf16 v[34:49], v[82:85], v[66:69], 0
	s_mov_b32 s100, 0xff000
	s_mov_b32 s101, 0
	v_lshl_add_u64 v[238:239], v[116:117], 0, s[100:101]
	global_load_dwordx4 v[106:109], v[238:239], off
	global_load_dwordx4 v[102:105], v[238:239], off offset:1024
	global_load_dwordx4 v[110:113], v[238:239], off offset:2048
	global_load_dwordx4 v[98:101], v[238:239], off offset:3072
	s_add_i32 s25, s30, s23
	s_mov_b64 s[18:19], -1
	v_mfma_f32_32x32x16_bf16 v[34:49], v[86:89], v[70:73], v[34:49]
	v_mfma_f32_32x32x16_bf16 v[34:49], v[90:93], v[74:77], v[34:49]
	v_mfma_f32_32x32x16_bf16 v[34:49], v[94:97], v[78:81], v[34:49]
	s_add_i32 s100, s24, 2
	s_cmp_lt_u32 s100, s21
	s_cbranch_scc0 .Lp2_noload
	global_load_dwordx4 v[82:85], v[116:117], off
	global_load_dwordx4 v[86:89], v[116:117], off offset:1024
	global_load_dwordx4 v[90:93], v[116:117], off offset:2048
	global_load_dwordx4 v[94:97], v[116:117], off offset:3072
